# v12 + state-scan phase: the 32-step recurrence's 64 loads all in flight before the dependent fma chain
# speedup vs baseline: 1.0073x; 1.0073x over previous
; __device__ __forceinline__ void hgrn_scan(int gtid, int gsize, const float* UBUF, const float* DTOT, float* SST, float* ohp) {
;     ...
;     for (int e = gtid; e < 8 * 16384; e += gsize) {
;         const int bh = e >> 14, idx = e & 16383, k = idx >> 7; float s = 0.f;
; #pragma unroll 8
;         for (int sc = 0; sc < 32; ++sc) { const int unit = bh * 32 + sc; SST[(size_t)unit * 16384 + idx] = s; s = DTOT[unit * 128 + k] * s + UBUF[(size_t)unit * 16384 + idx]; }
.LBB0_526:
	s_add_u32 s40, s26, 0x11600000
	s_addc_u32 s41, s27, 0
	s_add_u32 s42, s26, 0x12700000
	s_addc_u32 s43, s27, 0
	s_mov_b64 s[44:45], s[26:27]
	s_add_u32 s46, s26, 0x1000
	s_addc_u32 s47, s27, 0
	s_add_u32 s48, s26, 0x2000
	s_addc_u32 s49, s27, 0
	s_add_u32 s54, s26, 0x3000
	s_addc_u32 s55, s27, 0
	global_load_dword v120, v24, s[44:45]
	global_load_dword v66, v10, s[40:41]
	s_add_u32 s40, s40, 0x10000
	s_addc_u32 s41, s41, 0
	global_load_dword v121, v24, s[44:45] offset:512
	global_load_dword v67, v10, s[40:41]
	s_add_u32 s40, s40, 0x10000
	s_addc_u32 s41, s41, 0
	global_load_dword v122, v24, s[44:45] offset:1024
	global_load_dword v68, v10, s[40:41]
	s_add_u32 s40, s40, 0x10000
	s_addc_u32 s41, s41, 0
	global_load_dword v123, v24, s[44:45] offset:1536
	global_load_dword v69, v10, s[40:41]
	s_add_u32 s40, s40, 0x10000
	s_addc_u32 s41, s41, 0
	global_load_dword v124, v24, s[44:45] offset:2048
	global_load_dword v70, v10, s[40:41]
	s_add_u32 s40, s40, 0x10000
	s_addc_u32 s41, s41, 0
	global_load_dword v125, v24, s[44:45] offset:2560
	global_load_dword v71, v10, s[40:41]
	s_add_u32 s40, s40, 0x10000
	s_addc_u32 s41, s41, 0
	global_load_dword v126, v24, s[44:45] offset:3072
	global_load_dword v72, v10, s[40:41]
	s_add_u32 s40, s40, 0x10000
	s_addc_u32 s41, s41, 0
	global_load_dword v127, v24, s[44:45] offset:3584
	global_load_dword v73, v10, s[40:41]
	s_add_u32 s40, s40, 0x10000
	s_addc_u32 s41, s41, 0
	global_load_dword v128, v24, s[46:47]
	global_load_dword v74, v10, s[40:41]
	s_add_u32 s40, s40, 0x10000
	s_addc_u32 s41, s41, 0
	global_load_dword v129, v24, s[46:47] offset:512
	global_load_dword v75, v10, s[40:41]
	s_add_u32 s40, s40, 0x10000
	s_addc_u32 s41, s41, 0
	global_load_dword v130, v24, s[46:47] offset:1024
	global_load_dword v76, v10, s[40:41]
	s_add_u32 s40, s40, 0x10000
	s_addc_u32 s41, s41, 0
	global_load_dword v133, v24, s[46:47] offset:1536
	global_load_dword v77, v10, s[40:41]
	s_add_u32 s40, s40, 0x10000
	s_addc_u32 s41, s41, 0
	global_load_dword v134, v24, s[46:47] offset:2048
	global_load_dword v78, v10, s[40:41]
	s_add_u32 s40, s40, 0x10000
	s_addc_u32 s41, s41, 0
	global_load_dword v135, v24, s[46:47] offset:2560
	global_load_dword v79, v10, s[40:41]
	s_add_u32 s40, s40, 0x10000
	s_addc_u32 s41, s41, 0
	global_load_dword v136, v24, s[46:47] offset:3072
	global_load_dword v80, v10, s[40:41]
	s_add_u32 s40, s40, 0x10000
	s_addc_u32 s41, s41, 0
	global_load_dword v137, v24, s[46:47] offset:3584
	global_load_dword v81, v10, s[40:41]
	s_add_u32 s40, s40, 0x10000
	s_addc_u32 s41, s41, 0
	global_load_dword v138, v24, s[48:49]
	global_load_dword v82, v10, s[40:41]
	s_add_u32 s40, s40, 0x10000
	s_addc_u32 s41, s41, 0
	global_load_dword v139, v24, s[48:49] offset:512
	global_load_dword v83, v10, s[40:41]
	s_add_u32 s40, s40, 0x10000
	s_addc_u32 s41, s41, 0
	global_load_dword v140, v24, s[48:49] offset:1024
	global_load_dword v84, v10, s[40:41]
	s_add_u32 s40, s40, 0x10000
	s_addc_u32 s41, s41, 0
	global_load_dword v141, v24, s[48:49] offset:1536
	global_load_dword v85, v10, s[40:41]
	s_add_u32 s40, s40, 0x10000
	s_addc_u32 s41, s41, 0
	global_load_dword v142, v24, s[48:49] offset:2048
	global_load_dword v86, v10, s[40:41]
	s_add_u32 s40, s40, 0x10000
	s_addc_u32 s41, s41, 0
	global_load_dword v143, v24, s[48:49] offset:2560
	global_load_dword v87, v10, s[40:41]
	s_add_u32 s40, s40, 0x10000
	s_addc_u32 s41, s41, 0
	global_load_dword v144, v24, s[48:49] offset:3072
	global_load_dword v88, v10, s[40:41]
	s_add_u32 s40, s40, 0x10000
	s_addc_u32 s41, s41, 0
	global_load_dword v145, v24, s[48:49] offset:3584
	global_load_dword v89, v10, s[40:41]
	s_add_u32 s40, s40, 0x10000
	s_addc_u32 s41, s41, 0
	global_load_dword v146, v24, s[54:55]
	global_load_dword v90, v10, s[40:41]
	s_add_u32 s40, s40, 0x10000
	s_addc_u32 s41, s41, 0
	global_load_dword v52, v24, s[54:55] offset:512
	global_load_dword v91, v10, s[40:41]
	s_add_u32 s40, s40, 0x10000
	s_addc_u32 s41, s41, 0
	global_load_dword v53, v24, s[54:55] offset:1024
	global_load_dword v92, v10, s[40:41]
	s_add_u32 s40, s40, 0x10000
	s_addc_u32 s41, s41, 0
	global_load_dword v54, v24, s[54:55] offset:1536
	global_load_dword v93, v10, s[40:41]
	s_add_u32 s40, s40, 0x10000
	s_addc_u32 s41, s41, 0
	global_load_dword v55, v24, s[54:55] offset:2048
	global_load_dword v94, v10, s[40:41]
	s_add_u32 s40, s40, 0x10000
	s_addc_u32 s41, s41, 0
	global_load_dword v56, v24, s[54:55] offset:2560
	global_load_dword v95, v10, s[40:41]
	s_add_u32 s40, s40, 0x10000
	s_addc_u32 s41, s41, 0
	global_load_dword v57, v24, s[54:55] offset:3072
	global_load_dword v96, v10, s[40:41]
	s_add_u32 s40, s40, 0x10000
	s_addc_u32 s41, s41, 0
	global_load_dword v58, v24, s[54:55] offset:3584
	global_load_dword v97, v10, s[40:41]
	s_add_u32 s40, s40, 0x10000
	s_addc_u32 s41, s41, 0
	s_waitcnt vmcnt(0)
; __device__ __forceinline__ void hgrn_scan(int gtid, int gsize, const float* UBUF, const float* DTOT, float* SST, float* ohp) {
;     ...
;     for (int e = gtid; e < 8 * 16384; e += gsize) {
;         const int bh = e >> 14, idx = e & 16383, k = idx >> 7; float s = 0.f;
; #pragma unroll 8
;         for (int sc = 0; sc < 32; ++sc) { const int unit = bh * 32 + sc; SST[(size_t)unit * 16384 + idx] = s; s = DTOT[unit * 128 + k] * s + UBUF[(size_t)unit * 16384 + idx]; }
;         ohp[(size_t)bh * 16384 + idx] = s;
	global_store_dword v10, v28, s[42:43]
	s_add_u32 s42, s42, 0x10000
	s_addc_u32 s43, s43, 0
	v_fmac_f32_e32 v66, v28, v120
	global_store_dword v10, v66, s[42:43]
	s_add_u32 s42, s42, 0x10000
	s_addc_u32 s43, s43, 0
	v_fmac_f32_e32 v67, v66, v121
	global_store_dword v10, v67, s[42:43]
	s_add_u32 s42, s42, 0x10000
	s_addc_u32 s43, s43, 0
	v_fmac_f32_e32 v68, v67, v122
	global_store_dword v10, v68, s[42:43]
	s_add_u32 s42, s42, 0x10000
	s_addc_u32 s43, s43, 0
	v_fmac_f32_e32 v69, v68, v123
	global_store_dword v10, v69, s[42:43]
	s_add_u32 s42, s42, 0x10000
	s_addc_u32 s43, s43, 0
	v_fmac_f32_e32 v70, v69, v124
	global_store_dword v10, v70, s[42:43]
	s_add_u32 s42, s42, 0x10000
	s_addc_u32 s43, s43, 0
	v_fmac_f32_e32 v71, v70, v125
	global_store_dword v10, v71, s[42:43]
	s_add_u32 s42, s42, 0x10000
	s_addc_u32 s43, s43, 0
	v_fmac_f32_e32 v72, v71, v126
	global_store_dword v10, v72, s[42:43]
	s_add_u32 s42, s42, 0x10000
	s_addc_u32 s43, s43, 0
	v_fmac_f32_e32 v73, v72, v127
	global_store_dword v10, v73, s[42:43]
	s_add_u32 s42, s42, 0x10000
	s_addc_u32 s43, s43, 0
	v_fmac_f32_e32 v74, v73, v128
	global_store_dword v10, v74, s[42:43]
	s_add_u32 s42, s42, 0x10000
	s_addc_u32 s43, s43, 0
	v_fmac_f32_e32 v75, v74, v129
	global_store_dword v10, v75, s[42:43]
	s_add_u32 s42, s42, 0x10000
	s_addc_u32 s43, s43, 0
	v_fmac_f32_e32 v76, v75, v130
	global_store_dword v10, v76, s[42:43]
	s_add_u32 s42, s42, 0x10000
	s_addc_u32 s43, s43, 0
	v_fmac_f32_e32 v77, v76, v133
	global_store_dword v10, v77, s[42:43]
	s_add_u32 s42, s42, 0x10000
	s_addc_u32 s43, s43, 0
	v_fmac_f32_e32 v78, v77, v134
	global_store_dword v10, v78, s[42:43]
	s_add_u32 s42, s42, 0x10000
	s_addc_u32 s43, s43, 0
	v_fmac_f32_e32 v79, v78, v135
	global_store_dword v10, v79, s[42:43]
	s_add_u32 s42, s42, 0x10000
	s_addc_u32 s43, s43, 0
	v_fmac_f32_e32 v80, v79, v136
	global_store_dword v10, v80, s[42:43]
	s_add_u32 s42, s42, 0x10000
	s_addc_u32 s43, s43, 0
	v_fmac_f32_e32 v81, v80, v137
	global_store_dword v10, v81, s[42:43]
	s_add_u32 s42, s42, 0x10000
	s_addc_u32 s43, s43, 0
	v_fmac_f32_e32 v82, v81, v138
	global_store_dword v10, v82, s[42:43]
	s_add_u32 s42, s42, 0x10000
	s_addc_u32 s43, s43, 0
	v_fmac_f32_e32 v83, v82, v139
	global_store_dword v10, v83, s[42:43]
	s_add_u32 s42, s42, 0x10000
	s_addc_u32 s43, s43, 0
	v_fmac_f32_e32 v84, v83, v140
	global_store_dword v10, v84, s[42:43]
	s_add_u32 s42, s42, 0x10000
	s_addc_u32 s43, s43, 0
	v_fmac_f32_e32 v85, v84, v141
	global_store_dword v10, v85, s[42:43]
	s_add_u32 s42, s42, 0x10000
	s_addc_u32 s43, s43, 0
	v_fmac_f32_e32 v86, v85, v142
	global_store_dword v10, v86, s[42:43]
	s_add_u32 s42, s42, 0x10000
	s_addc_u32 s43, s43, 0
	v_fmac_f32_e32 v87, v86, v143
	global_store_dword v10, v87, s[42:43]
	s_add_u32 s42, s42, 0x10000
	s_addc_u32 s43, s43, 0
	v_fmac_f32_e32 v88, v87, v144
	global_store_dword v10, v88, s[42:43]
	s_add_u32 s42, s42, 0x10000
	s_addc_u32 s43, s43, 0
	v_fmac_f32_e32 v89, v88, v145
	global_store_dword v10, v89, s[42:43]
	s_add_u32 s42, s42, 0x10000
	s_addc_u32 s43, s43, 0
	v_fmac_f32_e32 v90, v89, v146
	global_store_dword v10, v90, s[42:43]
	s_add_u32 s42, s42, 0x10000
	s_addc_u32 s43, s43, 0
	v_fmac_f32_e32 v91, v90, v52
	global_store_dword v10, v91, s[42:43]
	s_add_u32 s42, s42, 0x10000
	s_addc_u32 s43, s43, 0
	v_fmac_f32_e32 v92, v91, v53
	global_store_dword v10, v92, s[42:43]
	s_add_u32 s42, s42, 0x10000
	s_addc_u32 s43, s43, 0
	v_fmac_f32_e32 v93, v92, v54
	global_store_dword v10, v93, s[42:43]
	s_add_u32 s42, s42, 0x10000
	s_addc_u32 s43, s43, 0
	v_fmac_f32_e32 v94, v93, v55
	global_store_dword v10, v94, s[42:43]
	s_add_u32 s42, s42, 0x10000
	s_addc_u32 s43, s43, 0
	v_fmac_f32_e32 v95, v94, v56
	global_store_dword v10, v95, s[42:43]
	s_add_u32 s42, s42, 0x10000
	s_addc_u32 s43, s43, 0
	v_fmac_f32_e32 v96, v95, v57
	global_store_dword v10, v96, s[42:43]
	s_add_u32 s42, s42, 0x10000
	s_addc_u32 s43, s43, 0
	v_fmac_f32_e32 v97, v96, v58
	v_mov_b32_e32 v28, v97
	v_ashrrev_i32_e32 v7, 31, v6
	v_and_b32_e32 v4, 0x3fff, v26
	v_lshlrev_b64 v[6:7], 16, v[6:7]
	v_add_u32_e32 v26, s1, v26
	v_lshl_add_u64 v[6:7], s[24:25], 0, v[6:7]
	v_lshlrev_b32_e32 v4, 2, v4
	v_cmp_lt_i32_e32 vcc, s2, v26
	v_lshl_add_u64 v[6:7], v[6:7], 0, v[4:5]
	s_or_b64 s[34:35], vcc, s[34:35]
	v_add_u16_e32 v27, s1, v27
	global_store_dword v[6:7], v28, off
	s_andn2_b64 exec, exec, s[34:35]
	s_cbranch_execnz .LBB0_525
